# adds P3 item-order split: half the workgroups start with token-MLP items and wrap to carry fix-up items; placement padded to +4 mod 64
# baseline (speedup 1.0000x reference)
; __device__ __forceinline__ void mlp_tile(const Ctx& C, int l, int ct, int hd) {
;     ...
;         for (int sw = 0; sw < 4; ++sw) { const int s = sw * 32 + (tid >> 4);
;             vv[sw] = *(const u32x4*)(vn + (size_t)(T.row0 + min(s, T.nvalid - 1)) * GW + hd * 128 + d8); }
; #pragma unroll
;         for (int sw = 0; sw < 4; ++sw) { const int s = sw * 32 + (tid >> 4); if (s >= T.nvalid) vv[sw] = (u32x4){0u, 0u, 0u, 0u}; }
;         if (wact) {
;             const bf16_t* wp = (const bf16_t*)(C.ws + WS_WSP) + ((size_t)(l * 8 + hd) * 128 + t) * 128 + 8 * fq;
; #pragma unroll
;             for (int kk = 0; kk < 4; ++kk) wfr[kk] = *(const bf16x8*)(wp + 32 * kk);
; #pragma unroll
;             for (int n = 0; n < 8; ++n) uw[n] = *(const u32x2*)(proj + (size_t)row * NPROJ + 2048 + hd * 128 + 16 * n + 4 * fq);
;             bs = C.in[16][(size_t)(l * 8 + hd) * 128 + t];
; __global__ void __launch_bounds__(NTHREADS, 2) mega(Args a) {
;     ...
;         if (RUN(ph)) { MKCTX();
;             { float* ssqY = (float*)(C.ws + WS_SSQY); for (int i = C.bid * NTHREADS + C.tid; i < MP; i += C.G * NTHREADS) ssqY[i] = 0.f; }
;             for (int rep = 0; rep < REP_MIX; ++rep)
;             for (int it = C.bid; it < 2 * NCT * 8; it += C.G) {
;                 if (it < 128 * 8) lru_fix_tile(C, l, it >> 3, it & 7); else if (it < NCT * 8) { LruHead H; load_lru_head(C, l, it & 7, H); lru_tile<2>(C, l, it >> 3, it & 7, H); } else mlp_tile(C, l, (it - NCT * 8) >> 3, it & 7);
;             }
.LBB0_908:
	s_or_b64 exec, exec, s[6:7]
	s_cmpk_gt_i32 s67, 0x8ff
	s_cbranch_scc1 .LBB0_1246
	v_and_b32_e32 v106, 15, v6
	v_lshlrev_b32_e32 v0, 4, v106
	v_lshl_add_u64 v[2:3], s[90:91], 0, v[0:1]
	s_mov_b64 s[8:9], 0x12a00000
	v_lshl_add_u64 v[112:113], v[2:3], 0, s[8:9]
	v_and_b32_e32 v2, 48, v6
	v_mov_b32_e32 v3, v1
	v_lshl_add_u64 v[4:5], s[90:91], 0, v[2:3]
	s_mov_b64 s[8:9], 0x5b00000
	v_lshl_add_u64 v[114:115], v[4:5], 0, s[8:9]
	s_movk_i32 s8, 0x880
	v_lshlrev_b32_e32 v107, 3, v106
	v_ashrrev_i32_e32 v110, 4, v6
	v_mad_u32_u24 v9, v106, s8, 0
	s_mov_b32 s8, 0x7ffffff8
	v_and_b32_e32 v3, 7, v110
	v_bitop3_b32 v10, v110, v107, s8 bitop3:0x6c
	v_add_u32_e32 v117, 32, v110
	v_or_b32_e32 v10, v10, v3
	s_lshl_b32 s3, s93, 14
	v_lshl_add_u32 v134, v10, 1, v9
	v_bitop3_b32 v10, v117, v107, s8 bitop3:0x6c
	v_writelane_b32 v249, s3, 53
	s_ashr_i32 s3, s2, 6
	v_add_u32_e32 v132, 64, v110
	v_or_b32_e32 v10, v10, v3
	s_lshl_b32 s6, s93, 10
	s_lshl_b32 s71, s93, 4
	s_lshl_b32 s36, s93, 16
	s_lshl_b32 s37, s93, 1
	s_lshl_b32 s38, s93, 12
	s_lshl_b32 s33, s3, 4
	v_lshl_add_u32 v135, v10, 1, v9
	v_bitop3_b32 v10, v132, v107, s8 bitop3:0x6c
	s_ashr_i32 s2, s2, 7
	v_add_u32_e32 v133, 0x60, v110
	v_or_b32_e32 v10, v10, v3
	s_cmp_gt_i32 s2, -1
	v_lshl_add_u32 v136, v10, 1, v9
	v_bitop3_b32 v10, v133, v107, s8 bitop3:0x6c
	s_cselect_b64 s[8:9], -1, 0
	s_min_u32 s2, s2, 3
	v_writelane_b32 v249, s93, 54
	s_add_i32 s2, s2, 1
	v_writelane_b32 v249, s8, 55
	s_cmp_gt_u32 s3, 1
	s_mov_b32 s7, s39
	v_writelane_b32 v249, s9, 56
	s_cselect_b64 s[8:9], -1, 0
	v_writelane_b32 v249, s8, 57
	s_cmp_lg_u32 s2, 2
	v_bfe_u32 v8, v6, 4, 2
	v_writelane_b32 v249, s9, 58
	s_cselect_b64 s[8:9], -1, 0
	v_writelane_b32 v249, s8, 59
	s_cmp_lg_u32 s2, 3
	s_cselect_b64 s[2:3], -1, 0
	v_writelane_b32 v249, s9, 60
	v_writelane_b32 v249, s2, 61
	s_ashr_i32 s28, s33, 31
	v_or_b32_e32 v3, v10, v3
	v_writelane_b32 v249, s3, 62
	s_mov_b64 s[2:3], 0x5a00000
	v_lshl_add_u64 v[118:119], v[4:5], 0, s[2:3]
	s_mov_b64 s[2:3], 0x5a80000
	v_lshl_add_u64 v[120:121], v[4:5], 0, s[2:3]
	s_lshl_b64 s[2:3], s[38:39], 2
	s_add_u32 s8, s44, s2
	s_addc_u32 s9, s45, s3
	s_lshl_b64 s[2:3], s[6:7], 2
	s_add_u32 s10, s46, s2
	s_addc_u32 s11, s47, s3
	s_add_u32 s12, s90, 0xa200000
	s_addc_u32 s13, s91, 0
	v_lshl_add_u32 v137, v3, 1, v9
	v_bfe_u32 v3, v6, 3, 1
	v_or_b32_e32 v18, 4, v8
	v_or_b32_e32 v26, 8, v8
	s_waitcnt vmcnt(0)
; #define LAS __attribute__((address_space(3)))
; __device__ __forceinline__ void mlp_tile(const Ctx& C, int l, int ct, int hd) {
;     ...
;         for (int sw = 0; sw < 4; ++sw) { const int s = sw * 32 + (tid >> 4); const u32x4 v = vv[sw];
;             const int sc = ((((s >> 3) ^ (tid & 15)) << 3) | (s & 7));
;             VT[(d8 + 0) * SX + sc] = (bf16_t)(v.x & 0xffffu); VT[(d8 + 1) * SX + sc] = (bf16_t)(v.x >> 16);
;             VT[(d8 + 2) * SX + sc] = (bf16_t)(v.y & 0xffffu); VT[(d8 + 3) * SX + sc] = (bf16_t)(v.y >> 16);
;             VT[(d8 + 4) * SX + sc] = (bf16_t)(v.z & 0xffffu); VT[(d8 + 5) * SX + sc] = (bf16_t)(v.z >> 16);
;             VT[(d8 + 6) * SX + sc] = (bf16_t)(v.w & 0xffffu); VT[(d8 + 7) * SX + sc] = (bf16_t)(v.w >> 16);
;         }
;     }
;     __syncthreads();
;     if (wact) {
;         const int nk = ((16 * w + 15) >> 5) + 1;
;         f32x4 acc[8];
; #pragma unroll
;         for (int n = 0; n < 8; ++n) acc[n] = (f32x4){0.f, 0.f, 0.f, 0.f};
; #pragma unroll
;         for (int kk = 0; kk < 4; ++kk) {
;             if (kk >= nk) break;
;             const bf16x8 wf = wfr[kk];
; #pragma unroll
;             for (int n = 0; n < 8; ++n) { const bf16x8 vf = *(const LAS bf16x8*)(VT + (16 * n + fr) * SX + (((4 * kk + fq) ^ (2 * n + (fr >> 3))) << 3));
;                 acc[n] = __builtin_amdgcn_mfma_f32_16x16x32_bf16(vf, wf, acc[n], 0, 0, 0); }
; __global__ void __launch_bounds__(NTHREADS, 2) mega(Args a) {
;     ...
;             for (int it = C.bid; it < 2 * NCT * 8; it += C.G) {
;                 if (it < 128 * 8) lru_fix_tile(C, l, it >> 3, it & 7); else if (it < NCT * 8) { LruHead H; load_lru_head(C, l, it & 7, H); lru_tile<2>(C, l, it >> 3, it & 7, H); } else mlp_tile(C, l, (it - NCT * 8) >> 3, it & 7);
;             }
	v_or_b32_e32 v34, 12, v8
	s_add_u32 s14, s90, 0x19800000
	v_xor_b32_e32 v10, v3, v8
	v_bitop3_b32 v11, v3, v8, 2 bitop3:0x36
	v_bitop3_b32 v12, v3, v8, 4 bitop3:0x36
	v_bitop3_b32 v13, v3, v8, 6 bitop3:0x36
	v_bitop3_b32 v14, v3, v8, 8 bitop3:0x36
	v_bitop3_b32 v15, v3, v8, 10 bitop3:0x36
	v_bitop3_b32 v16, v3, v8, 12 bitop3:0x36
	v_bitop3_b32 v17, v3, v8, 14 bitop3:0x36
	v_bitop3_b32 v19, v3, v8, 4 bitop3:0x1e
	v_bitop3_b32 v20, v3, v18, 2 bitop3:0x36
	v_bitop3_b32 v21, v3, v8, 4 bitop3:0x14
	v_bitop3_b32 v22, v3, v18, 6 bitop3:0x36
	v_bitop3_b32 v23, v3, v18, 8 bitop3:0x36
	v_bitop3_b32 v24, v3, v18, 10 bitop3:0x36
	v_bitop3_b32 v25, v3, v18, 12 bitop3:0x36
	v_bitop3_b32 v18, v3, v18, 14 bitop3:0x36
	v_bitop3_b32 v27, v3, v8, 8 bitop3:0x1e
	v_bitop3_b32 v28, v3, v26, 2 bitop3:0x36
	v_bitop3_b32 v29, v3, v26, 4 bitop3:0x36
	v_bitop3_b32 v30, v3, v26, 6 bitop3:0x36
	v_bitop3_b32 v31, v3, v8, 8 bitop3:0x14
	v_bitop3_b32 v32, v3, v26, 10 bitop3:0x36
	v_bitop3_b32 v33, v3, v26, 12 bitop3:0x36
	v_bitop3_b32 v26, v3, v26, 14 bitop3:0x36
	v_bitop3_b32 v35, v3, v8, 12 bitop3:0x1e
	v_bitop3_b32 v36, v3, v34, 2 bitop3:0x36
	v_bitop3_b32 v37, v3, v34, 4 bitop3:0x36
	v_bitop3_b32 v38, v3, v34, 6 bitop3:0x36
	v_bitop3_b32 v39, v3, v34, 8 bitop3:0x36
	v_bitop3_b32 v40, v3, v34, 10 bitop3:0x36
	v_bitop3_b32 v41, v3, v8, 12 bitop3:0x14
	v_bitop3_b32 v3, v3, v34, 14 bitop3:0x36
	s_addc_u32 s15, s91, 0
	v_and_b32_e32 v7, 63, v6
	v_lshlrev_b32_e32 v34, 4, v3
	v_and_b32_e32 v3, 3, v6
	s_movk_i32 s2, 0x60
	s_add_u32 s16, s90, 0x5c80000
	v_and_or_b32 v3, v107, s2, v3
	v_cmp_lt_u32_e64 s[2:3], 31, v7
	s_addc_u32 s17, s91, 0
	v_or_b32_e32 v108, s33, v106
	v_writelane_b32 v249, s2, 63
	s_add_u32 s18, s90, 0x15200000
	s_movk_i32 s20, 0x110
	v_add_u32_e32 v4, 0, v2
	v_mul_u32_u24_e32 v5, 0x110, v3
	v_lshlrev_b32_e32 v2, 1, v108
	v_mul_u32_u24_e32 v3, 0x2200, v8
	v_writelane_b32 v248, s3, 0
	s_addc_u32 s19, s91, 0
	s_movk_i32 s2, 0x7f
	v_add3_u32 v138, 0, v2, v3
	v_cmp_eq_u32_e64 s[54:55], s2, v110
	s_add_u32 s7, s88, 0x880c000
	v_cmp_eq_u32_e64 s[56:57], s2, v117
	v_cmp_eq_u32_e64 s[58:59], s2, v132
	v_cmp_eq_u32_e64 s[60:61], s2, v133
	v_mad_u64_u32 v[2:3], s[2:3], v110, s20, v[0:1]
	s_addc_u32 s92, s89, 0
	s_add_i32 s93, s71, 0xffffff80
	s_lshl_b32 s27, s67, 7
	s_add_i32 s2, 0, 0x8800
	v_mad_u32_u24 v9, v106, s20, 0
	v_lshlrev_b32_e32 v10, 4, v10
	v_lshlrev_b32_e32 v11, 4, v11
	v_lshlrev_b32_e32 v12, 4, v12
	v_lshlrev_b32_e32 v13, 4, v13
	v_lshlrev_b32_e32 v14, 4, v14
	v_lshlrev_b32_e32 v15, 4, v15
	v_lshlrev_b32_e32 v16, 4, v16
	v_lshlrev_b32_e32 v17, 4, v17
	v_lshlrev_b32_e32 v19, 4, v19
	v_lshlrev_b32_e32 v20, 4, v20
	v_lshlrev_b32_e32 v21, 4, v21
	v_lshlrev_b32_e32 v22, 4, v22
	v_lshlrev_b32_e32 v23, 4, v23
	v_lshlrev_b32_e32 v24, 4, v24
	v_lshlrev_b32_e32 v25, 4, v25
	v_lshlrev_b32_e32 v18, 4, v18
	v_lshlrev_b32_e32 v27, 4, v27
	v_lshlrev_b32_e32 v28, 4, v28
	v_lshlrev_b32_e32 v29, 4, v29
	v_lshlrev_b32_e32 v30, 4, v30
	v_lshlrev_b32_e32 v31, 4, v31
	v_lshlrev_b32_e32 v32, 4, v32
	v_lshlrev_b32_e32 v33, 4, v33
	v_lshlrev_b32_e32 v26, 4, v26
	v_lshlrev_b32_e32 v35, 4, v35
	v_lshlrev_b32_e32 v36, 4, v36
	v_lshlrev_b32_e32 v37, 4, v37
	v_lshlrev_b32_e32 v38, 4, v38
	v_lshlrev_b32_e32 v39, 4, v39
	v_lshlrev_b32_e32 v40, 4, v40
	v_lshlrev_b32_e32 v41, 4, v41
	v_cmp_gt_u32_e64 s[40:41], 16, v7
	v_cmp_gt_u32_e64 s[42:43], 32, v7
	v_lshlrev_b32_e32 v7, 3, v6
	s_add_u32 s20, s90, 0x5b80000
	v_ashrrev_i32_e32 v109, 31, v108
	v_lshlrev_b32_e32 v116, 2, v8
	v_cmp_eq_u32_e64 s[46:47], 3, v8
	v_cmp_eq_u32_e64 s[44:45], 1, v8
	v_lshl_add_u64 v[122:123], s[14:15], 0, v[0:1]
	v_cmp_eq_u32_e64 s[50:51], 0, v106
	v_and_b32_e32 v124, 0x7f, v6
	v_ashrrev_i32_e32 v139, 7, v6
	v_mov_b32_e32 v125, v1
	v_cmp_gt_i32_e64 s[52:53], s30, v6
	v_lshl_add_u32 v140, v6, 2, 0
	v_lshl_add_u32 v141, v106, 5, 0
	v_ashrrev_i32_e32 v111, 31, v110
	v_add_u32_e32 v142, 0, v2
	v_add_u32_e32 v143, s2, v2
	s_addc_u32 s21, s91, 0
	v_add_u32_e32 v144, v9, v10
	v_add_u32_e32 v145, v9, v11
	v_add_u32_e32 v146, v9, v12
	v_add_u32_e32 v147, v9, v13
	v_add_u32_e32 v148, v9, v14
	v_add_u32_e32 v149, v9, v15
	v_add_u32_e32 v150, v9, v16
	v_add_u32_e32 v151, v9, v17
	v_add_u32_e32 v152, v9, v19
	v_add_u32_e32 v153, v9, v20
	v_add_u32_e32 v154, v9, v21
	v_add_u32_e32 v155, v9, v22
	v_add_u32_e32 v156, v9, v23
	v_add_u32_e32 v157, v9, v24
	v_add_u32_e32 v158, v9, v25
	v_add_u32_e32 v159, v9, v18
	v_add_u32_e32 v160, v9, v27
	v_add_u32_e32 v161, v9, v28
	v_add_u32_e32 v162, v9, v29
	v_add_u32_e32 v163, v9, v30
	v_add_u32_e32 v164, v9, v31
	v_add_u32_e32 v165, v9, v32
	v_add_u32_e32 v166, v9, v33
	v_add_u32_e32 v167, v9, v26
	v_add_u32_e32 v168, v9, v35
	v_add_u32_e32 v169, v9, v36
	v_add_u32_e32 v170, v9, v37
	v_add_u32_e32 v171, v9, v38
	v_add_u32_e32 v172, v9, v39
	v_add_u32_e32 v173, v9, v40
	v_add_u32_e32 v174, v9, v41
	v_add_u32_e32 v175, v9, v34
	v_add_u32_e32 v176, v4, v5
	v_add_u32_e32 v177, 0, v7
	s_mov_b32 s100, -1
	s_mov_b32 s101, 0
	s_cmp_lg_u32 s74, 0x100
	s_cbranch_scc1 .Lmy_p3_a
	s_bitcmp1_b32 s67, 3
	s_cbranch_scc0 .Lmy_p3_a
	s_addk_i32 s67, 0x400
	s_add_i32 s27, s27, 0x20000
	s_mov_b32 s100, s67
	s_mov_b32 s101, 1
.Lmy_p3_a:
	s_branch .LBB0_912
.LBB0_910:
	s_or_b64 exec, exec, s[24:25]
	s_waitcnt lgkmcnt(0)
	s_barrier
.LBB0_911:
	v_readlane_b32 s2, v249, 37
	s_add_i32 s67, s67, s74
	s_add_i32 s27, s27, s2
	s_cmpk_lt_i32 s67, 0x900
	s_cbranch_scc1 .Lmy_p3_cont
	s_cmp_eq_u32 s101, 0
	s_cbranch_scc1 .LBB0_1245
	s_addk_i32 s67, 0xf700
	s_sub_i32 s27, s27, 0x48000
.Lmy_p3_cont:
	s_cmp_eq_u32 s67, s100
	s_cbranch_scc1 .LBB0_1245

; __device__ __forceinline__ void lru_fix_tile(const Ctx& C, int l, int ct, int hd) {
;     ...
;         *(u32x4*)(outab + row * D + chg) = o;
;         if ((tid & 15) == 0) unsafeAtomicAdd(sab + 2 * row, ss);
;         if (T.c == 63 && t == 127) { float* o2 = C.out + O_LRUP + (size_t)(l * 2 + T.sidx) * GW + chg;
;             *(f32x4*)o2 = (f32x4){h[0], h[1], h[2], h[3]}; *(f32x4*)(o2 + 4) = (f32x4){h[4], h[5], h[6], h[7]}; }
;     }
;     __syncthreads();
.LBB0_1243:
	s_or_b64 exec, exec, s[24:25]
	s_and_b64 s[2:3], s[62:63], s[60:61]
	s_and_saveexec_b64 s[24:25], s[2:3]
	s_cbranch_execz .LBB0_910
	s_add_u32 s2, s7, s22
	s_addc_u32 s3, s92, s23
	global_store_dwordx4 v58, v[6:9], s[2:3]
	global_store_dwordx4 v58, v[2:5], s[2:3] offset:16
	s_branch .LBB0_910
	s_nop 0
	s_nop 0
	s_nop 0
	s_nop 0
	s_nop 0
	s_nop 0
	s_nop 0
	s_nop 0
	s_nop 0
	s_nop 0
	s_nop 0
	s_nop 0
	s_nop 0
